# v21: conformer conv 31-tap loop software-pipelined across passes (first 12 LDS reads of the next pass issued during the current one)
# speedup vs baseline: 1.0249x; 1.0010x over previous
; #define LDS_WAIT() asm volatile("s_waitcnt lgkmcnt(0)" ::: "memory")
; __device__ __forceinline__ void conv_unit_p(const bf16* __restrict__ Z, bf16* __restrict__ CAT, float* __restrict__ newc, ...
;     ...
; #pragma unroll 1
;     for (int tq = 0; tq < 32; tq += 4) {
;         float acc[4] = {bias, bias, bias, bias};
; #pragma unroll
;         for (int r = 0; r < 34; ++r) { const float gvv = gL[(tq + r) * 64 + lane];
; #pragma unroll
;             for (int q = 0; q < 4; ++q) { const int k = r - q; if (k >= 0 && k <= 30) acc[q] += wk[k] * gvv; } }
;         LDS_WAIT();
; #pragma unroll
;         for (int q = 0; q < 4; ++q) gL[(tq + q) * 64 + lane] = acc[q];
;     }
.LBB0_409:
	s_or_b64 exec, exec, s[6:7]
	s_waitcnt lgkmcnt(0)
	s_nop 0
	v_lshl_add_u32 v0, v124, 2, s69
	s_mov_b32 s2, -4
	ds_read2st64_b32 v[136:137], v0 offset1:1
	ds_read2st64_b32 v[138:139], v0 offset0:2 offset1:3
	ds_read2st64_b32 v[140:141], v0 offset0:4 offset1:5
	ds_read2st64_b32 v[142:143], v0 offset0:6 offset1:7
	ds_read2st64_b32 v[144:145], v0 offset0:8 offset1:9
	ds_read2st64_b32 v[146:147], v0 offset0:10 offset1:11
	ds_read2st64_b32 v[148:149], v0 offset0:12 offset1:13
	ds_read2st64_b32 v[150:151], v0 offset0:14 offset1:15
	ds_read2st64_b32 v[152:153], v0 offset0:16 offset1:17
	ds_read2st64_b32 v[154:155], v0 offset0:18 offset1:19
	ds_read2st64_b32 v[156:157], v0 offset0:20 offset1:21
	ds_read2st64_b32 v[158:159], v0 offset0:22 offset1:23
	ds_read_b32 v190, v0
	ds_read_b32 v190, v0
.LBB0_410:
	s_add_i32 s2, s2, 4
	v_add_u32_e32 v4, 0x400, v0
	s_waitcnt lgkmcnt(13)
	v_fma_f32 v1, v87, v136, v118
	v_fmac_f32_e32 v1, v88, v137
	v_fma_f32 v2, v87, v137, v118
	ds_read2st64_b32 v[160:161], v0 offset0:24 offset1:25
	s_waitcnt lgkmcnt(13)
	v_fmac_f32_e32 v1, v89, v138
	v_fmac_f32_e32 v2, v88, v138
	v_fma_f32 v3, v87, v138, v118
	v_fmac_f32_e32 v1, v90, v139
	v_fmac_f32_e32 v2, v89, v139
	v_fmac_f32_e32 v3, v88, v139
	v_fma_f32 v5, v87, v139, v118
	ds_read2st64_b32 v[162:163], v0 offset0:26 offset1:27
	s_waitcnt lgkmcnt(13)
	v_fmac_f32_e32 v1, v95, v140
	v_fmac_f32_e32 v2, v90, v140
	v_fmac_f32_e32 v3, v89, v140
	v_fmac_f32_e32 v5, v88, v140
	v_fmac_f32_e32 v1, v91, v141
	v_fmac_f32_e32 v2, v95, v141
	v_fmac_f32_e32 v3, v90, v141
	v_fmac_f32_e32 v5, v89, v141
	ds_read2st64_b32 v[164:165], v0 offset0:28 offset1:29
	s_waitcnt lgkmcnt(13)
	v_fmac_f32_e32 v1, v92, v142
	v_fmac_f32_e32 v2, v91, v142
	v_fmac_f32_e32 v3, v95, v142
	v_fmac_f32_e32 v5, v90, v142
	v_fmac_f32_e32 v1, v93, v143
	v_fmac_f32_e32 v2, v92, v143
	v_fmac_f32_e32 v3, v91, v143
	v_fmac_f32_e32 v5, v95, v143
	ds_read2st64_b32 v[166:167], v0 offset0:30 offset1:31
	s_waitcnt lgkmcnt(13)
	v_fmac_f32_e32 v1, v96, v144
	v_fmac_f32_e32 v2, v93, v144
	v_fmac_f32_e32 v3, v92, v144
	v_fmac_f32_e32 v5, v91, v144
	v_fmac_f32_e32 v1, v97, v145
	v_fmac_f32_e32 v2, v96, v145
	v_fmac_f32_e32 v3, v93, v145
	v_fmac_f32_e32 v5, v92, v145
	ds_read2st64_b32 v[188:189], v0 offset0:32 offset1:33
	s_waitcnt lgkmcnt(13)
	v_fmac_f32_e32 v1, v98, v146
	v_fmac_f32_e32 v2, v97, v146
	v_fmac_f32_e32 v3, v96, v146
	v_fmac_f32_e32 v5, v93, v146
	v_fmac_f32_e32 v1, v99, v147
	v_fmac_f32_e32 v2, v98, v147
	v_fmac_f32_e32 v3, v97, v147
	v_fmac_f32_e32 v5, v96, v147
	ds_read2st64_b32 v[136:137], v4 offset1:1
	s_waitcnt lgkmcnt(13)
	v_fmac_f32_e32 v1, v100, v148
	v_fmac_f32_e32 v2, v99, v148
	v_fmac_f32_e32 v3, v98, v148
	v_fmac_f32_e32 v5, v97, v148
	v_fmac_f32_e32 v1, v94, v149
	v_fmac_f32_e32 v2, v100, v149
	v_fmac_f32_e32 v3, v99, v149
	v_fmac_f32_e32 v5, v98, v149
	ds_read2st64_b32 v[138:139], v4 offset0:2 offset1:3
	s_waitcnt lgkmcnt(13)
	v_fmac_f32_e32 v1, v110, v150
	v_fmac_f32_e32 v2, v94, v150
	v_fmac_f32_e32 v3, v100, v150
	v_fmac_f32_e32 v5, v99, v150
	v_fmac_f32_e32 v1, v111, v151
	v_fmac_f32_e32 v2, v110, v151
	v_fmac_f32_e32 v3, v94, v151
	v_fmac_f32_e32 v5, v100, v151
	ds_read2st64_b32 v[140:141], v4 offset0:4 offset1:5
	s_waitcnt lgkmcnt(13)
	v_fmac_f32_e32 v1, v101, v152
	v_fmac_f32_e32 v2, v111, v152
	v_fmac_f32_e32 v3, v110, v152
	v_fmac_f32_e32 v5, v94, v152
	v_fmac_f32_e32 v1, v102, v153
	v_fmac_f32_e32 v2, v101, v153
	v_fmac_f32_e32 v3, v111, v153
	v_fmac_f32_e32 v5, v110, v153
	ds_read2st64_b32 v[142:143], v4 offset0:6 offset1:7
	s_waitcnt lgkmcnt(13)
	v_fmac_f32_e32 v1, v103, v154
	v_fmac_f32_e32 v2, v102, v154
	v_fmac_f32_e32 v3, v101, v154
	v_fmac_f32_e32 v5, v111, v154
	v_fmac_f32_e32 v1, v104, v155
	v_fmac_f32_e32 v2, v103, v155
	v_fmac_f32_e32 v3, v102, v155
	v_fmac_f32_e32 v5, v101, v155
	ds_read2st64_b32 v[144:145], v4 offset0:8 offset1:9
	s_waitcnt lgkmcnt(13)
	v_fmac_f32_e32 v1, v105, v156
	v_fmac_f32_e32 v2, v104, v156
	v_fmac_f32_e32 v3, v103, v156
	v_fmac_f32_e32 v5, v102, v156
	v_fmac_f32_e32 v1, v112, v157
	v_fmac_f32_e32 v2, v105, v157
	v_fmac_f32_e32 v3, v104, v157
	v_fmac_f32_e32 v5, v103, v157
	ds_read2st64_b32 v[146:147], v4 offset0:10 offset1:11
	s_waitcnt lgkmcnt(13)
	v_fmac_f32_e32 v1, v113, v158
	v_fmac_f32_e32 v2, v112, v158
	v_fmac_f32_e32 v3, v105, v158
	v_fmac_f32_e32 v5, v104, v158
	v_fmac_f32_e32 v1, v114, v159
	v_fmac_f32_e32 v2, v113, v159
	v_fmac_f32_e32 v3, v112, v159
	v_fmac_f32_e32 v5, v105, v159
	ds_read2st64_b32 v[148:149], v4 offset0:12 offset1:13
	s_waitcnt lgkmcnt(11)
	v_fmac_f32_e32 v1, v106, v160
	v_fmac_f32_e32 v2, v114, v160
	v_fmac_f32_e32 v3, v113, v160
	v_fmac_f32_e32 v5, v112, v160
	v_fmac_f32_e32 v1, v107, v161
	v_fmac_f32_e32 v2, v106, v161
	v_fmac_f32_e32 v3, v114, v161
	v_fmac_f32_e32 v5, v113, v161
	ds_read2st64_b32 v[150:151], v4 offset0:14 offset1:15
	s_waitcnt lgkmcnt(11)
	v_fmac_f32_e32 v1, v108, v162
	v_fmac_f32_e32 v2, v107, v162
	v_fmac_f32_e32 v3, v106, v162
	v_fmac_f32_e32 v5, v114, v162
	v_fmac_f32_e32 v1, v109, v163
	v_fmac_f32_e32 v2, v108, v163
	v_fmac_f32_e32 v3, v107, v163
	v_fmac_f32_e32 v5, v106, v163
	ds_read2st64_b32 v[152:153], v4 offset0:16 offset1:17
	s_waitcnt lgkmcnt(11)
	v_fmac_f32_e32 v1, v115, v164
	v_fmac_f32_e32 v2, v109, v164
	v_fmac_f32_e32 v3, v108, v164
	v_fmac_f32_e32 v5, v107, v164
	v_fmac_f32_e32 v1, v116, v165
	v_fmac_f32_e32 v2, v115, v165
	v_fmac_f32_e32 v3, v109, v165
	v_fmac_f32_e32 v5, v108, v165
	ds_read2st64_b32 v[154:155], v4 offset0:18 offset1:19
	s_waitcnt lgkmcnt(11)
	v_fmac_f32_e32 v2, v116, v166
	v_fmac_f32_e32 v3, v115, v166
	v_fmac_f32_e32 v5, v109, v166
	v_fmac_f32_e32 v1, v117, v166
	v_fmac_f32_e32 v2, v117, v167
	v_fmac_f32_e32 v3, v116, v167
	v_fmac_f32_e32 v5, v115, v167
	ds_read2st64_b32 v[156:157], v4 offset0:20 offset1:21
	s_waitcnt lgkmcnt(11)
	v_fmac_f32_e32 v5, v116, v188
	v_fmac_f32_e32 v3, v117, v188
	v_fmac_f32_e32 v5, v117, v189
	ds_read2st64_b32 v[158:159], v4 offset0:22 offset1:23
	s_cmp_lt_u32 s2, 28
	ds_write2st64_b32 v0, v1, v2 offset1:1
	ds_write2st64_b32 v0, v3, v5 offset0:2 offset1:3
	v_mov_b32_e32 v0, v4
	s_cbranch_scc1 .LBB0_410
; #define LAS __attribute__((address_space(3)))
; __device__ __forceinline__ float sum8(float v) { v += dpp_get<0xB1, 0xF>(v); v += dpp_get<0x4E, 0xF>(v); v += dpp_get<0x141, 0xF>(v); return v; }
; __device__ __forceinline__ v4u pack8(const float (&f)[8]) { v4u w; w.x = pg8::cvt_pk_bf16(f[0], f[1]); w.y = pg8::cvt_pk_bf16(f[2], f[3]); w.z = pg8::cvt_pk_bf16(f[4], f[5]); w.w = pg8::cvt_pk_bf16(f[6], f[7]); return w; }
; __device__ __forceinline__ float sigm(float x) { return __builtin_amdgcn_rcpf(1.f + __builtin_amdgcn_exp2f(-1.44269504f * x)); }
; #define LDS_WAIT() asm volatile("s_waitcnt lgkmcnt(0)" ::: "memory")
; __device__ __forceinline__ void conv_unit_p(const bf16* __restrict__ Z, bf16* __restrict__ CAT, float* __restrict__ newc, ...
;     ...
;     LDS_WAIT();
;     float gg[8], bb[8];
; #pragma unroll
;     for (int i = 0; i < 8; ++i) { gg[i] = lg[c0 + i]; bb[i] = lb[c0 + i]; }
;     bf16* ob = CAT + (rowbase + t0) * DP + 256 + c0;
; #pragma unroll
;     for (int j = 0; j < 4; ++j) { const int r = 8 * j + rr; const f32x4 a = *(const LAS f32x4*)(gL + r * 64 + cg * 8), b = *(const LAS f32x4*)(gL + r * 64 + cg * 8 + 4);
;         float x[8] = {a[0], a[1], a[2], a[3], b[0], b[1], b[2], b[3]};
;         const float mean = sum8(((x[0] + x[1]) + (x[2] + x[3])) + ((x[4] + x[5]) + (x[6] + x[7]))) * (1.f / 64.f);
;         float q = 0.f;
; #pragma unroll
;         for (int i = 0; i < 8; ++i) { x[i] -= mean; q += x[i] * x[i]; }
;         const float rstd = rsqrtf(sum8(q) * (1.f / 64.f) + EPS);
; #pragma unroll
;         for (int i = 0; i < 8; ++i) { const float yy = x[i] * rstd * gg[i] + bb[i]; x[i] = yy * sigm(yy); }
;         *(v4u*)(ob + r * DP) = pack8(x); }
	v_mov_b64_e32 v[0:1], s[70:71]
	s_waitcnt lgkmcnt(0)
	v_mad_u64_u32 v[16:17], s[6:7], s84, v181, v[0:1]
	global_load_dwordx4 v[4:7], v128, s[54:55] offset:16
	global_load_dwordx4 v[12:15], v128, s[54:55]
	global_load_dwordx4 v[0:3], v128, s[26:27] offset:16
	global_load_dwordx4 v[8:11], v128, s[26:27]
	ds_read_b128 v[18:21], v67
	ds_read_b128 v[22:25], v67 offset:16
	s_or_b32 s4, s4, s74
	s_lshl_b64 s[4:5], s[4:5], 11
	v_lshl_add_u64 v[16:17], v[16:17], 0, s[4:5]
	s_waitcnt lgkmcnt(1)
	v_mov_b32_e32 v26, v18
	s_waitcnt lgkmcnt(0)
	v_mov_b32_e32 v27, v22
	v_mov_b32_e32 v28, v19
	v_mov_b32_e32 v29, v23
	v_pk_add_f32 v[26:27], v[26:27], v[28:29]
	v_mov_b32_e32 v28, v20
	v_mov_b32_e32 v29, v24
	v_mov_b32_e32 v30, v21
	v_mov_b32_e32 v31, v25
	v_pk_add_f32 v[28:29], v[28:29], v[30:31]
	v_mov_b32_e32 v65, v129
	v_pk_add_f32 v[26:27], v[26:27], v[28:29]
	v_lshl_add_u64 v[16:17], v[16:17], 0, v[64:65]
	v_add_f32_e32 v26, v26, v27
	s_mov_b64 s[4:5], 0x900200
	v_lshl_add_u64 v[16:17], v[16:17], 0, s[4:5]
	v_add_f32_dpp v26, v26, v26 quad_perm:[1,0,3,2] row_mask:0xf bank_mask:0xf bound_ctrl:1
	s_mov_b32 s2, 36
	v_readlane_b32 s70, v254, 58
	v_add_f32_dpp v26, v26, v26 quad_perm:[2,3,0,1] row_mask:0xf bank_mask:0xf bound_ctrl:1
	s_nop 1
	v_add_f32_dpp v26, v26, v26 row_half_mirror row_mask:0xf bank_mask:0xf bound_ctrl:1
	v_mul_f32_e32 v26, 0x3c800000, v26
	v_pk_add_f32 v[28:29], v[18:19], v[26:27] op_sel_hi:[1,0] neg_lo:[0,1] neg_hi:[0,1]
	v_pk_add_f32 v[20:21], v[20:21], v[26:27] op_sel_hi:[1,0] neg_lo:[0,1] neg_hi:[0,1]
	v_pk_mul_f32 v[30:31], v[28:29], v[28:29]
	v_pk_mul_f32 v[32:33], v[20:21], v[20:21]
	v_pk_add_f32 v[22:23], v[22:23], v[26:27] op_sel_hi:[1,0] neg_lo:[0,1] neg_hi:[0,1]
	v_pk_add_f32 v[18:19], v[24:25], v[26:27] op_sel_hi:[1,0] neg_lo:[0,1] neg_hi:[0,1]
	v_add_f32_e32 v26, v30, v31
	v_add_f32_e32 v26, v32, v26
	v_pk_mul_f32 v[34:35], v[22:23], v[22:23]
	v_add_f32_e32 v26, v33, v26
	v_add_f32_e32 v26, v34, v26
	v_pk_mul_f32 v[24:25], v[18:19], v[18:19]
	v_add_f32_e32 v26, v35, v26
	v_add_f32_e32 v24, v24, v26
	v_add_f32_e32 v24, v25, v24
	s_nop 1
	v_add_f32_dpp v24, v24, v24 quad_perm:[1,0,3,2] row_mask:0xf bank_mask:0xf bound_ctrl:1
	s_nop 1
	v_add_f32_dpp v24, v24, v24 quad_perm:[2,3,0,1] row_mask:0xf bank_mask:0xf bound_ctrl:1
	s_nop 1
	v_add_f32_dpp v24, v24, v24 row_half_mirror row_mask:0xf bank_mask:0xf bound_ctrl:1
	v_fmamk_f32 v24, v24, 0x3c800000, v168
	v_cmp_gt_f32_e32 vcc, s79, v24
	v_mul_f32_e32 v25, 0x4b800000, v24
	s_nop 0
	v_cndmask_b32_e32 v24, v24, v25, vcc
	v_rsq_f32_e32 v24, v24
	s_nop 0
	v_mul_f32_e32 v25, 0x45800000, v24
	v_cndmask_b32_e32 v24, v24, v25, vcc
	v_mul_f32_e32 v25, v28, v24
	v_mul_f32_e32 v20, v20, v24
	v_mul_f32_e32 v21, v21, v24
	v_mul_f32_e32 v22, v22, v24
	v_mul_f32_e32 v23, v23, v24
	v_mul_f32_e32 v18, v18, v24
	s_waitcnt vmcnt(1)
	v_fma_f32 v22, v4, v22, v0
	s_waitcnt vmcnt(0)
	v_fma_f32 v25, v12, v25, v8
	v_mul_f32_e32 v26, 0xbfb8aa3b, v25
	v_exp_f32_e32 v26, v26
	v_fma_f32 v20, v14, v20, v10
	v_fma_f32 v21, v15, v21, v11
	v_fma_f32 v23, v5, v23, v1
	v_add_f32_e32 v26, 1.0, v26
	v_rcp_f32_e32 v26, v26
	v_fma_f32 v18, v6, v18, v2
	v_mul_f32_e32 v25, v25, v26
	v_mul_f32_e32 v26, v29, v24
	v_fma_f32 v26, v13, v26, v9
	v_mul_f32_e32 v27, 0xbfb8aa3b, v26
	v_exp_f32_e32 v27, v27
	s_nop 0
	v_add_f32_e32 v27, 1.0, v27
	v_rcp_f32_e32 v27, v27
	s_nop 0
	v_mul_f32_e32 v26, v26, v27
	v_mul_f32_e32 v27, 0xbfb8aa3b, v20
	v_exp_f32_e32 v27, v27
	s_nop 0
	v_add_f32_e32 v27, 1.0, v27
	v_rcp_f32_e32 v27, v27
	s_nop 0
	v_mul_f32_e32 v20, v20, v27
	v_mul_f32_e32 v27, 0xbfb8aa3b, v21
	v_exp_f32_e32 v27, v27
	s_nop 0
	v_add_f32_e32 v27, 1.0, v27
	v_rcp_f32_e32 v27, v27
	s_nop 0
	v_mul_f32_e32 v21, v21, v27
	v_mul_f32_e32 v27, 0xbfb8aa3b, v22
	v_exp_f32_e32 v27, v27
	s_nop 0
	v_add_f32_e32 v27, 1.0, v27
	v_rcp_f32_e32 v27, v27
	s_nop 0
	v_mul_f32_e32 v22, v22, v27
	v_mul_f32_e32 v27, 0xbfb8aa3b, v23
	v_exp_f32_e32 v27, v27
	s_nop 0
	v_add_f32_e32 v27, 1.0, v27
	v_rcp_f32_e32 v27, v27
	s_nop 0
	v_mul_f32_e32 v23, v23, v27
	v_mul_f32_e32 v27, 0xbfb8aa3b, v18
	v_exp_f32_e32 v27, v27
	s_nop 0
	v_add_f32_e32 v27, 1.0, v27
	v_rcp_f32_e32 v27, v27
	s_nop 0
	v_mul_f32_e32 v27, v18, v27
	v_mul_f32_e32 v18, v19, v24
	v_fma_f32 v18, v7, v18, v3
	v_mul_f32_e32 v19, 0xbfb8aa3b, v18
	v_exp_f32_e32 v19, v19
	s_nop 0
	v_add_f32_e32 v19, 1.0, v19
	v_rcp_f32_e32 v19, v19
	s_nop 0
	v_mul_f32_e32 v24, v18, v19
	v_cvt_pk_bf16_f32 v18, v25, v26
	v_cvt_pk_bf16_f32 v19, v20, v21
	v_cvt_pk_bf16_f32 v20, v22, v23
	v_lshlrev_b32_e32 v22, 10, v86
	v_ashrrev_i32_e32 v23, 31, v22
	v_lshl_add_u64 v[22:23], v[22:23], 1, v[16:17]
	v_cvt_pk_bf16_f32 v21, v27, v24
	global_store_dwordx4 v[22:23], v[18:21], off
	ds_read_b128 v[18:21], v56
	ds_read_b128 v[22:25], v56 offset:16
	s_waitcnt lgkmcnt(1)
	v_mov_b32_e32 v26, v18
	s_waitcnt lgkmcnt(0)
; #define LAS __attribute__((address_space(3)))
; __device__ __forceinline__ float sum8(float v) { v += dpp_get<0xB1, 0xF>(v); v += dpp_get<0x4E, 0xF>(v); v += dpp_get<0x141, 0xF>(v); return v; }
; __device__ __forceinline__ v4u pack8(const float (&f)[8]) { v4u w; w.x = pg8::cvt_pk_bf16(f[0], f[1]); w.y = pg8::cvt_pk_bf16(f[2], f[3]); w.z = pg8::cvt_pk_bf16(f[4], f[5]); w.w = pg8::cvt_pk_bf16(f[6], f[7]); return w; }
; __device__ __forceinline__ float sigm(float x) { return __builtin_amdgcn_rcpf(1.f + __builtin_amdgcn_exp2f(-1.44269504f * x)); }
; __device__ __forceinline__ void conv_unit_p(const bf16* __restrict__ Z, bf16* __restrict__ CAT, float* __restrict__ newc, ...
;     ...
;     for (int j = 0; j < 4; ++j) { const int r = 8 * j + rr; const f32x4 a = *(const LAS f32x4*)(gL + r * 64 + cg * 8), b = *(const LAS f32x4*)(gL + r * 64 + cg * 8 + 4);
;         float x[8] = {a[0], a[1], a[2], a[3], b[0], b[1], b[2], b[3]};
;         const float mean = sum8(((x[0] + x[1]) + (x[2] + x[3])) + ((x[4] + x[5]) + (x[6] + x[7]))) * (1.f / 64.f);
;         float q = 0.f;
; #pragma unroll
;         for (int i = 0; i < 8; ++i) { x[i] -= mean; q += x[i] * x[i]; }
;         const float rstd = rsqrtf(sum8(q) * (1.f / 64.f) + EPS);
; #pragma unroll
;         for (int i = 0; i < 8; ++i) { const float yy = x[i] * rstd * gg[i] + bb[i]; x[i] = yy * sigm(yy); }
;         *(v4u*)(ob + r * DP) = pack8(x); }
	v_mov_b32_e32 v27, v22
	v_mov_b32_e32 v28, v19
	v_mov_b32_e32 v29, v23
	v_pk_add_f32 v[26:27], v[26:27], v[28:29]
	v_mov_b32_e32 v28, v20
	v_mov_b32_e32 v29, v24
	v_mov_b32_e32 v30, v21
	v_mov_b32_e32 v31, v25
	v_pk_add_f32 v[28:29], v[28:29], v[30:31]
	s_nop 0
	v_pk_add_f32 v[26:27], v[26:27], v[28:29]
	s_nop 0
	v_add_f32_e32 v26, v26, v27
	s_nop 1
	v_add_f32_dpp v26, v26, v26 quad_perm:[1,0,3,2] row_mask:0xf bank_mask:0xf bound_ctrl:1
	s_nop 1
	v_add_f32_dpp v26, v26, v26 quad_perm:[2,3,0,1] row_mask:0xf bank_mask:0xf bound_ctrl:1
	s_nop 1
	v_add_f32_dpp v26, v26, v26 row_half_mirror row_mask:0xf bank_mask:0xf bound_ctrl:1
	v_mul_f32_e32 v26, 0x3c800000, v26
	v_pk_add_f32 v[18:19], v[18:19], v[26:27] op_sel_hi:[1,0] neg_lo:[0,1] neg_hi:[0,1]
	v_pk_add_f32 v[20:21], v[20:21], v[26:27] op_sel_hi:[1,0] neg_lo:[0,1] neg_hi:[0,1]
	v_pk_mul_f32 v[28:29], v[18:19], v[18:19]
	v_pk_mul_f32 v[30:31], v[20:21], v[20:21]
	v_add_f32_e32 v28, v28, v29
	v_pk_add_f32 v[22:23], v[22:23], v[26:27] op_sel_hi:[1,0] neg_lo:[0,1] neg_hi:[0,1]
	v_add_f32_e32 v28, v30, v28
	v_pk_mul_f32 v[32:33], v[22:23], v[22:23]
	v_add_f32_e32 v28, v31, v28
	v_pk_add_f32 v[24:25], v[24:25], v[26:27] op_sel_hi:[1,0] neg_lo:[0,1] neg_hi:[0,1]
	v_add_f32_e32 v28, v32, v28
	v_pk_mul_f32 v[26:27], v[24:25], v[24:25]
	v_add_f32_e32 v28, v33, v28
	v_add_f32_e32 v26, v26, v28
	v_add_f32_e32 v26, v27, v26
	s_nop 1
	v_add_f32_dpp v26, v26, v26 quad_perm:[1,0,3,2] row_mask:0xf bank_mask:0xf bound_ctrl:1
	s_nop 1
	v_add_f32_dpp v26, v26, v26 quad_perm:[2,3,0,1] row_mask:0xf bank_mask:0xf bound_ctrl:1
	s_nop 1
	v_add_f32_dpp v26, v26, v26 row_half_mirror row_mask:0xf bank_mask:0xf bound_ctrl:1
	v_fmamk_f32 v26, v26, 0x3c800000, v168
	v_cmp_gt_f32_e32 vcc, s79, v26
	v_mul_f32_e32 v27, 0x4b800000, v26
	s_nop 0
	v_cndmask_b32_e32 v26, v26, v27, vcc
	v_rsq_f32_e32 v26, v26
	s_nop 0
	v_mul_f32_e32 v27, 0x45800000, v26
	v_cndmask_b32_e32 v26, v26, v27, vcc
	v_mul_f32_e32 v18, v18, v26
	v_fma_f32 v18, v12, v18, v8
	v_mul_f32_e32 v27, 0xbfb8aa3b, v18
	v_exp_f32_e32 v27, v27
	v_mul_f32_e32 v19, v19, v26
	v_fma_f32 v19, v13, v19, v9
	v_mul_f32_e32 v20, v20, v26
	v_add_f32_e32 v27, 1.0, v27
	v_rcp_f32_e32 v27, v27
	v_fma_f32 v20, v14, v20, v10
	v_mul_f32_e32 v21, v21, v26
	v_fma_f32 v21, v15, v21, v11
	v_mul_f32_e32 v18, v18, v27
	v_mul_f32_e32 v27, 0xbfb8aa3b, v19
	v_exp_f32_e32 v27, v27
	v_mul_f32_e32 v22, v22, v26
	v_fma_f32 v22, v4, v22, v0
	v_mul_f32_e32 v23, v23, v26
	v_add_f32_e32 v27, 1.0, v27
	v_rcp_f32_e32 v27, v27
	v_fma_f32 v23, v5, v23, v1
	v_mul_f32_e32 v24, v24, v26
	v_mul_f32_e32 v25, v25, v26
	v_mul_f32_e32 v19, v19, v27
	v_mul_f32_e32 v27, 0xbfb8aa3b, v20
	v_exp_f32_e32 v27, v27
	v_fma_f32 v24, v6, v24, v2
	v_fma_f32 v25, v7, v25, v3
	v_mul_f32_e32 v26, 0xbfb8aa3b, v25
	v_add_f32_e32 v27, 1.0, v27
	v_rcp_f32_e32 v27, v27
	v_exp_f32_e32 v26, v26
	v_cvt_pk_bf16_f32 v18, v18, v19
	v_mul_f32_e32 v20, v20, v27
	v_mul_f32_e32 v27, 0xbfb8aa3b, v21
	v_exp_f32_e32 v27, v27
	v_add_f32_e32 v26, 1.0, v26
	v_rcp_f32_e32 v26, v26
	v_add_f32_e32 v27, 1.0, v27
	v_rcp_f32_e32 v27, v27
	v_mul_f32_e32 v25, v25, v26
	v_mul_f32_e32 v21, v21, v27
	v_mul_f32_e32 v27, 0xbfb8aa3b, v22
	v_exp_f32_e32 v27, v27
	v_cvt_pk_bf16_f32 v19, v20, v21
	s_nop 0
	v_add_f32_e32 v27, 1.0, v27
	v_rcp_f32_e32 v27, v27
	s_nop 0
	v_mul_f32_e32 v22, v22, v27
	v_mul_f32_e32 v27, 0xbfb8aa3b, v23
	v_exp_f32_e32 v27, v27
	s_nop 0
	v_add_f32_e32 v27, 1.0, v27
	v_rcp_f32_e32 v27, v27
	s_nop 0
	v_mul_f32_e32 v23, v23, v27
	v_mul_f32_e32 v27, 0xbfb8aa3b, v24
	v_exp_f32_e32 v27, v27
	v_cvt_pk_bf16_f32 v20, v22, v23
	v_lshlrev_b32_e32 v22, 10, v85
	v_ashrrev_i32_e32 v23, 31, v22
	v_add_f32_e32 v27, 1.0, v27
	v_rcp_f32_e32 v27, v27
	v_lshl_add_u64 v[22:23], v[22:23], 1, v[16:17]
	v_mul_f32_e32 v24, v24, v27
	v_cvt_pk_bf16_f32 v21, v24, v25
	global_store_dwordx4 v[22:23], v[18:21], off
	ds_read_b128 v[18:21], v48
	ds_read_b128 v[22:25], v48 offset:16
	s_waitcnt lgkmcnt(1)
	v_mov_b32_e32 v26, v18
	s_waitcnt lgkmcnt(0)
	v_mov_b32_e32 v27, v22
	v_mov_b32_e32 v28, v19
	v_mov_b32_e32 v29, v23
	v_pk_add_f32 v[26:27], v[26:27], v[28:29]
	v_mov_b32_e32 v28, v20
	v_mov_b32_e32 v29, v24
	v_mov_b32_e32 v30, v21
	v_mov_b32_e32 v31, v25
	v_pk_add_f32 v[28:29], v[28:29], v[30:31]
	s_nop 0
	v_pk_add_f32 v[26:27], v[26:27], v[28:29]
	s_nop 0
	v_add_f32_e32 v26, v26, v27
	s_nop 1
	v_add_f32_dpp v26, v26, v26 quad_perm:[1,0,3,2] row_mask:0xf bank_mask:0xf bound_ctrl:1
	s_nop 1
	v_add_f32_dpp v26, v26, v26 quad_perm:[2,3,0,1] row_mask:0xf bank_mask:0xf bound_ctrl:1
	s_nop 1
	v_add_f32_dpp v26, v26, v26 row_half_mirror row_mask:0xf bank_mask:0xf bound_ctrl:1
	v_mul_f32_e32 v26, 0x3c800000, v26
	v_pk_add_f32 v[18:19], v[18:19], v[26:27] op_sel_hi:[1,0] neg_lo:[0,1] neg_hi:[0,1]
	v_pk_add_f32 v[20:21], v[20:21], v[26:27] op_sel_hi:[1,0] neg_lo:[0,1] neg_hi:[0,1]
	v_pk_mul_f32 v[28:29], v[18:19], v[18:19]
	v_pk_mul_f32 v[30:31], v[20:21], v[20:21]
	v_add_f32_e32 v28, v28, v29
	v_pk_add_f32 v[22:23], v[22:23], v[26:27] op_sel_hi:[1,0] neg_lo:[0,1] neg_hi:[0,1]
	v_add_f32_e32 v28, v30, v28
	v_pk_mul_f32 v[32:33], v[22:23], v[22:23]
	v_add_f32_e32 v28, v31, v28
	v_pk_add_f32 v[24:25], v[24:25], v[26:27] op_sel_hi:[1,0] neg_lo:[0,1] neg_hi:[0,1]
	v_add_f32_e32 v28, v32, v28
	v_pk_mul_f32 v[26:27], v[24:25], v[24:25]
	v_add_f32_e32 v28, v33, v28
	v_add_f32_e32 v26, v26, v28
	v_add_f32_e32 v26, v27, v26
	s_nop 1
	v_add_f32_dpp v26, v26, v26 quad_perm:[1,0,3,2] row_mask:0xf bank_mask:0xf bound_ctrl:1
	s_nop 1
	v_add_f32_dpp v26, v26, v26 quad_perm:[2,3,0,1] row_mask:0xf bank_mask:0xf bound_ctrl:1
	s_nop 1
	v_add_f32_dpp v26, v26, v26 row_half_mirror row_mask:0xf bank_mask:0xf bound_ctrl:1
; #define LAS __attribute__((address_space(3)))
; __device__ __forceinline__ float sum8(float v) { v += dpp_get<0xB1, 0xF>(v); v += dpp_get<0x4E, 0xF>(v); v += dpp_get<0x141, 0xF>(v); return v; }
; __device__ __forceinline__ v4u pack8(const float (&f)[8]) { v4u w; w.x = pg8::cvt_pk_bf16(f[0], f[1]); w.y = pg8::cvt_pk_bf16(f[2], f[3]); w.z = pg8::cvt_pk_bf16(f[4], f[5]); w.w = pg8::cvt_pk_bf16(f[6], f[7]); return w; }
; __device__ __forceinline__ float sigm(float x) { return __builtin_amdgcn_rcpf(1.f + __builtin_amdgcn_exp2f(-1.44269504f * x)); }
; #define LDS_WAIT() asm volatile("s_waitcnt lgkmcnt(0)" ::: "memory")
; __device__ __forceinline__ void conv_unit_p(const bf16* __restrict__ Z, bf16* __restrict__ CAT, float* __restrict__ newc, ...
;     ...
;     for (int j = 0; j < 4; ++j) { const int r = 8 * j + rr; const f32x4 a = *(const LAS f32x4*)(gL + r * 64 + cg * 8), b = *(const LAS f32x4*)(gL + r * 64 + cg * 8 + 4);
;         float x[8] = {a[0], a[1], a[2], a[3], b[0], b[1], b[2], b[3]};
;         const float mean = sum8(((x[0] + x[1]) + (x[2] + x[3])) + ((x[4] + x[5]) + (x[6] + x[7]))) * (1.f / 64.f);
;         float q = 0.f;
; #pragma unroll
;         for (int i = 0; i < 8; ++i) { x[i] -= mean; q += x[i] * x[i]; }
;         const float rstd = rsqrtf(sum8(q) * (1.f / 64.f) + EPS);
; #pragma unroll
;         for (int i = 0; i < 8; ++i) { const float yy = x[i] * rstd * gg[i] + bb[i]; x[i] = yy * sigm(yy); }
;         *(v4u*)(ob + r * DP) = pack8(x); }
;     LDS_WAIT();
	v_fmamk_f32 v26, v26, 0x3c800000, v168
	v_cmp_gt_f32_e32 vcc, s79, v26
	v_mul_f32_e32 v27, 0x4b800000, v26
	s_nop 0
	v_cndmask_b32_e32 v26, v26, v27, vcc
	v_rsq_f32_e32 v26, v26
	s_nop 0
	v_mul_f32_e32 v27, 0x45800000, v26
	v_cndmask_b32_e32 v26, v26, v27, vcc
	v_mul_f32_e32 v18, v18, v26
	v_fma_f32 v18, v12, v18, v8
	v_mul_f32_e32 v27, 0xbfb8aa3b, v18
	v_exp_f32_e32 v27, v27
	v_mul_f32_e32 v19, v19, v26
	v_fma_f32 v19, v13, v19, v9
	v_mul_f32_e32 v20, v20, v26
	v_add_f32_e32 v27, 1.0, v27
	v_rcp_f32_e32 v27, v27
	v_fma_f32 v20, v14, v20, v10
	v_mul_f32_e32 v21, v21, v26
	v_fma_f32 v21, v15, v21, v11
	v_mul_f32_e32 v18, v18, v27
	v_mul_f32_e32 v27, 0xbfb8aa3b, v19
	v_exp_f32_e32 v27, v27
	v_mul_f32_e32 v22, v22, v26
	v_fma_f32 v22, v4, v22, v0
	v_mul_f32_e32 v23, v23, v26
	v_add_f32_e32 v27, 1.0, v27
	v_rcp_f32_e32 v27, v27
	v_fma_f32 v23, v5, v23, v1
	v_mul_f32_e32 v24, v24, v26
	v_mul_f32_e32 v25, v25, v26
	v_mul_f32_e32 v19, v19, v27
	v_mul_f32_e32 v27, 0xbfb8aa3b, v20
	v_exp_f32_e32 v27, v27
	v_fma_f32 v24, v6, v24, v2
	v_fma_f32 v25, v7, v25, v3
	v_mul_f32_e32 v26, 0xbfb8aa3b, v25
	v_add_f32_e32 v27, 1.0, v27
	v_rcp_f32_e32 v27, v27
	v_exp_f32_e32 v26, v26
	v_cvt_pk_bf16_f32 v18, v18, v19
	v_mul_f32_e32 v20, v20, v27
	v_mul_f32_e32 v27, 0xbfb8aa3b, v21
	v_exp_f32_e32 v27, v27
	v_add_f32_e32 v26, 1.0, v26
	v_rcp_f32_e32 v26, v26
	v_add_f32_e32 v27, 1.0, v27
	v_rcp_f32_e32 v27, v27
	v_mul_f32_e32 v25, v25, v26
	v_mul_f32_e32 v21, v21, v27
	v_mul_f32_e32 v27, 0xbfb8aa3b, v22
	v_exp_f32_e32 v27, v27
	v_cvt_pk_bf16_f32 v19, v20, v21
	s_nop 0
	v_add_f32_e32 v27, 1.0, v27
	v_rcp_f32_e32 v27, v27
	s_nop 0
	v_mul_f32_e32 v22, v22, v27
	v_mul_f32_e32 v27, 0xbfb8aa3b, v23
	v_exp_f32_e32 v27, v27
	s_nop 0
	v_add_f32_e32 v27, 1.0, v27
	v_rcp_f32_e32 v27, v27
	s_nop 0
	v_mul_f32_e32 v23, v23, v27
	v_mul_f32_e32 v27, 0xbfb8aa3b, v24
	v_exp_f32_e32 v27, v27
	v_cvt_pk_bf16_f32 v20, v22, v23
	v_lshlrev_b32_e32 v22, 10, v83
	v_ashrrev_i32_e32 v23, 31, v22
	v_add_f32_e32 v27, 1.0, v27
	v_rcp_f32_e32 v27, v27
	v_lshl_add_u64 v[22:23], v[22:23], 1, v[16:17]
	v_mul_f32_e32 v24, v24, v27
	v_cvt_pk_bf16_f32 v21, v24, v25
	global_store_dwordx4 v[22:23], v[18:21], off
	ds_read_b128 v[18:21], v40
	ds_read_b128 v[22:25], v40 offset:16
	s_waitcnt lgkmcnt(1)
	v_mov_b32_e32 v26, v18
	s_waitcnt lgkmcnt(0)
	v_mov_b32_e32 v27, v22
	v_mov_b32_e32 v28, v19
	v_mov_b32_e32 v29, v23
	v_pk_add_f32 v[26:27], v[26:27], v[28:29]
	v_mov_b32_e32 v28, v20
	v_mov_b32_e32 v29, v24
	v_mov_b32_e32 v30, v21
	v_mov_b32_e32 v31, v25
	v_pk_add_f32 v[28:29], v[28:29], v[30:31]
	s_nop 0
	v_pk_add_f32 v[26:27], v[26:27], v[28:29]
	s_nop 0
	v_add_f32_e32 v26, v26, v27
	s_nop 1
	v_add_f32_dpp v26, v26, v26 quad_perm:[1,0,3,2] row_mask:0xf bank_mask:0xf bound_ctrl:1
	s_nop 1
	v_add_f32_dpp v26, v26, v26 quad_perm:[2,3,0,1] row_mask:0xf bank_mask:0xf bound_ctrl:1
	s_nop 1
	v_add_f32_dpp v26, v26, v26 row_half_mirror row_mask:0xf bank_mask:0xf bound_ctrl:1
	v_mul_f32_e32 v26, 0x3c800000, v26
	v_pk_add_f32 v[18:19], v[18:19], v[26:27] op_sel_hi:[1,0] neg_lo:[0,1] neg_hi:[0,1]
	v_pk_add_f32 v[20:21], v[20:21], v[26:27] op_sel_hi:[1,0] neg_lo:[0,1] neg_hi:[0,1]
	v_pk_mul_f32 v[28:29], v[18:19], v[18:19]
	v_pk_mul_f32 v[30:31], v[20:21], v[20:21]
	v_add_f32_e32 v28, v28, v29
	v_pk_add_f32 v[22:23], v[22:23], v[26:27] op_sel_hi:[1,0] neg_lo:[0,1] neg_hi:[0,1]
	v_add_f32_e32 v28, v30, v28
	v_pk_mul_f32 v[32:33], v[22:23], v[22:23]
	v_add_f32_e32 v28, v31, v28
	v_pk_add_f32 v[24:25], v[24:25], v[26:27] op_sel_hi:[1,0] neg_lo:[0,1] neg_hi:[0,1]
	v_add_f32_e32 v28, v32, v28
	v_pk_mul_f32 v[26:27], v[24:25], v[24:25]
	v_add_f32_e32 v28, v33, v28
	v_add_f32_e32 v26, v26, v28
	v_add_f32_e32 v26, v27, v26
	s_nop 1
	v_add_f32_dpp v26, v26, v26 quad_perm:[1,0,3,2] row_mask:0xf bank_mask:0xf bound_ctrl:1
	s_nop 1
	v_add_f32_dpp v26, v26, v26 quad_perm:[2,3,0,1] row_mask:0xf bank_mask:0xf bound_ctrl:1
	s_nop 1
	v_add_f32_dpp v26, v26, v26 row_half_mirror row_mask:0xf bank_mask:0xf bound_ctrl:1
	v_fmamk_f32 v26, v26, 0x3c800000, v168
	v_cmp_gt_f32_e32 vcc, s79, v26
	v_mul_f32_e32 v27, 0x4b800000, v26
	s_nop 0
	v_cndmask_b32_e32 v26, v26, v27, vcc
	v_rsq_f32_e32 v26, v26
	s_nop 0
	v_mul_f32_e32 v27, 0x45800000, v26
	v_cndmask_b32_e32 v26, v26, v27, vcc
	v_mul_f32_e32 v18, v18, v26
	v_fma_f32 v8, v12, v18, v8
	v_mul_f32_e32 v12, 0xbfb8aa3b, v8
	v_exp_f32_e32 v12, v12
	s_nop 0
	v_add_f32_e32 v12, 1.0, v12
	v_rcp_f32_e32 v12, v12
	s_nop 0
	v_mul_f32_e32 v8, v8, v12
	v_mul_f32_e32 v12, v19, v26
	v_fma_f32 v9, v13, v12, v9
	v_mul_f32_e32 v12, 0xbfb8aa3b, v9
	v_exp_f32_e32 v12, v12
	s_nop 0
	v_add_f32_e32 v12, 1.0, v12
	v_rcp_f32_e32 v12, v12
	s_nop 0
	v_mul_f32_e32 v9, v9, v12
	v_mul_f32_e32 v12, v20, v26
	v_fma_f32 v10, v14, v12, v10
	v_mul_f32_e32 v12, 0xbfb8aa3b, v10
	v_exp_f32_e32 v12, v12
	s_nop 0
	v_add_f32_e32 v12, 1.0, v12
	v_rcp_f32_e32 v12, v12
	s_nop 0
	v_mul_f32_e32 v10, v10, v12
	v_mul_f32_e32 v12, v21, v26
	v_fmac_f32_e32 v11, v15, v12
	v_mul_f32_e32 v12, 0xbfb8aa3b, v11
	v_exp_f32_e32 v12, v12
	s_nop 0
	v_add_f32_e32 v12, 1.0, v12
	v_rcp_f32_e32 v12, v12
	s_nop 0
	v_mul_f32_e32 v11, v11, v12
	v_mul_f32_e32 v12, v22, v26
	v_fma_f32 v0, v4, v12, v0
	v_mul_f32_e32 v4, 0xbfb8aa3b, v0
	v_exp_f32_e32 v4, v4
	s_nop 0
	v_add_f32_e32 v4, 1.0, v4
	v_rcp_f32_e32 v4, v4
	s_nop 0
	v_mul_f32_e32 v4, v0, v4
	v_mul_f32_e32 v0, v23, v26
	v_fma_f32 v0, v5, v0, v1
	v_mul_f32_e32 v1, 0xbfb8aa3b, v0
	v_exp_f32_e32 v1, v1
	s_nop 0
	v_add_f32_e32 v1, 1.0, v1
	v_rcp_f32_e32 v1, v1
	s_nop 0
	v_mul_f32_e32 v5, v0, v1
	v_mul_f32_e32 v0, v24, v26
	v_fma_f32 v0, v6, v0, v2
	v_mul_f32_e32 v1, 0xbfb8aa3b, v0
	v_exp_f32_e32 v1, v1
	s_nop 0
	v_add_f32_e32 v1, 1.0, v1
	v_rcp_f32_e32 v1, v1
	s_nop 0
	v_mul_f32_e32 v6, v0, v1
	v_mul_f32_e32 v0, v25, v26
	v_fmac_f32_e32 v3, v7, v0
	v_mul_f32_e32 v0, 0xbfb8aa3b, v3
	v_exp_f32_e32 v0, v0
	s_nop 0
	v_add_f32_e32 v0, 1.0, v0
	v_rcp_f32_e32 v0, v0
	s_nop 0
	v_mul_f32_e32 v3, v3, v0
	v_cvt_pk_bf16_f32 v0, v8, v9
	v_cvt_pk_bf16_f32 v1, v10, v11
	v_cvt_pk_bf16_f32 v2, v4, v5
	v_lshlrev_b32_e32 v4, 10, v81
	v_ashrrev_i32_e32 v5, 31, v4
	v_lshl_add_u64 v[4:5], v[4:5], 1, v[16:17]
	v_cvt_pk_bf16_f32 v3, v6, v3
	global_store_dwordx4 v[4:5], v[0:3], off
	s_waitcnt lgkmcnt(0)
